# S6 epilogue: the 8 row-sumsq loads issued together up front, no vmcnt(0) between the ACT stores
# speedup vs baseline: 1.0484x; 1.0038x over previous
.LBB0_1413:
	v_lshl_add_u32 v144, s8, 8, v152
	v_ashrrev_i32_e32 v145, 31, v144
	v_lshl_add_u64 v[150:151], v[144:145], 2, s[10:11]
	global_load_dword v145, v[150:151], off
	global_load_dword v226, v[150:151], off offset:64
	global_load_dword v227, v[150:151], off offset:128
	global_load_dword v228, v[150:151], off offset:192
	global_load_dword v229, v[150:151], off offset:512
	global_load_dword v230, v[150:151], off offset:576
	global_load_dword v231, v[150:151], off offset:640
	global_load_dword v232, v[150:151], off offset:704
	v_lshl_add_u32 v146, s9, 7, v154
	v_or_b32_e32 v162, 16, v144
	v_mov_b64_e32 v[148:149], s[12:13]
	v_ashrrev_i32_e32 v147, 31, v146
	v_mad_i64_i32 v[160:161], s[4:5], v144, s42, v[148:149]
	v_lshlrev_b64 v[146:147], 1, v[146:147]
	v_lshl_add_u64 v[160:161], v[160:161], 0, v[146:147]
	s_waitcnt vmcnt(0) lgkmcnt(0)
	v_fmamk_f32 v145, v145, 0x3a000000, v158
	s_nop 1
	v_ashrrev_i32_e32 v163, 31, v162
	s_nop 1
	s_nop 1
	s_nop 1
	v_lshl_add_u64 v[164:165], v[162:163], 2, s[10:11]
	v_rsq_f32_e32 v166, v145
	s_nop 0
	v_pk_mul_f32 v[126:127], v[126:127], v[166:167] op_sel_hi:[1,0]
	v_pk_mul_f32 v[124:125], v[124:125], v[166:167] op_sel_hi:[1,0]
	v_pk_mul_f32 v[122:123], v[122:123], v[166:167] op_sel_hi:[1,0]
	v_pk_mul_f32 v[120:121], v[120:121], v[166:167] op_sel_hi:[1,0]
	v_pk_mul_f32 v[116:117], v[116:117], v[166:167] op_sel_hi:[1,0]
	v_pk_mul_f32 v[118:119], v[118:119], v[166:167] op_sel_hi:[1,0]
	v_pk_mul_f32 v[112:113], v[112:113], v[166:167] op_sel_hi:[1,0]
	v_pk_mul_f32 v[114:115], v[114:115], v[166:167] op_sel_hi:[1,0]
	v_pk_mul_f32 v[166:167], v[124:125], s[18:19] op_sel_hi:[1,0]
	v_pk_mul_f32 v[118:119], v[126:127], v[118:119]
	v_pk_mul_f32 v[116:117], v[124:125], v[116:117]
	v_pk_mul_f32 v[124:125], v[126:127], s[18:19] op_sel_hi:[1,0]
	v_pk_mul_f32 v[126:127], v[120:121], s[18:19] op_sel_hi:[1,0]
	v_pk_mul_f32 v[112:113], v[120:121], v[112:113]
	v_pk_mul_f32 v[120:121], v[122:123], s[18:19] op_sel_hi:[1,0]
	v_pk_mul_f32 v[114:115], v[122:123], v[114:115]
	v_exp_f32_e32 v122, v166
	v_exp_f32_e32 v123, v167
	v_exp_f32_e32 v124, v124
	v_exp_f32_e32 v125, v125
	v_exp_f32_e32 v126, v126
	v_exp_f32_e32 v127, v127
	v_exp_f32_e32 v120, v120
	v_exp_f32_e32 v121, v121
	v_pk_add_f32 v[122:123], v[122:123], 1.0 op_sel_hi:[1,0]
	v_pk_add_f32 v[124:125], v[124:125], 1.0 op_sel_hi:[1,0]
	v_pk_add_f32 v[126:127], v[126:127], 1.0 op_sel_hi:[1,0]
	v_pk_add_f32 v[120:121], v[120:121], 1.0 op_sel_hi:[1,0]
	v_rcp_f32_e32 v122, v122
	v_rcp_f32_e32 v123, v123
	v_rcp_f32_e32 v124, v124
	v_rcp_f32_e32 v125, v125
	v_rcp_f32_e32 v126, v126
	v_rcp_f32_e32 v127, v127
	v_rcp_f32_e32 v120, v120
	v_rcp_f32_e32 v121, v121
	v_pk_mul_f32 v[116:117], v[116:117], v[122:123]
	v_pk_mul_f32 v[118:119], v[118:119], v[124:125]
	v_pk_mul_f32 v[122:123], v[112:113], v[126:127]
	v_pk_mul_f32 v[120:121], v[114:115], v[120:121]
	v_cvt_pk_bf16_f32 v112, v116, v117
	v_cvt_pk_bf16_f32 v113, v118, v119
	v_cvt_pk_bf16_f32 v114, v122, v123
	s_nop 0
	v_cvt_pk_bf16_f32 v115, v120, v121
	global_store_dwordx4 v[160:161], v[112:115], off
	s_nop 1
	v_mov_b32_e32 v113, v226
	s_nop 0
	v_or_b32_e32 v112, 32, v144
	s_waitcnt lgkmcnt(0)
	v_fmamk_f32 v113, v113, 0x3a000000, v158
	v_rsq_f32_e32 v118, v113
	s_nop 1
	v_ashrrev_i32_e32 v113, 31, v112
	v_mad_i64_i32 v[114:115], s[4:5], v162, s42, v[148:149]
	v_lshl_add_u64 v[114:115], v[114:115], 0, v[146:147]
	s_nop 0
	s_nop 1
	s_nop 1
	v_lshl_add_u64 v[116:117], v[112:113], 2, s[10:11]
	s_nop 0
	v_pk_mul_f32 v[110:111], v[110:111], v[118:119] op_sel_hi:[1,0]
	v_pk_mul_f32 v[108:109], v[108:109], v[118:119] op_sel_hi:[1,0]
	v_pk_mul_f32 v[106:107], v[106:107], v[118:119] op_sel_hi:[1,0]
	v_pk_mul_f32 v[104:105], v[104:105], v[118:119] op_sel_hi:[1,0]
	v_pk_mul_f32 v[100:101], v[100:101], v[118:119] op_sel_hi:[1,0]
	v_pk_mul_f32 v[102:103], v[102:103], v[118:119] op_sel_hi:[1,0]
	v_pk_mul_f32 v[96:97], v[96:97], v[118:119] op_sel_hi:[1,0]
	v_pk_mul_f32 v[98:99], v[98:99], v[118:119] op_sel_hi:[1,0]
	v_pk_mul_f32 v[118:119], v[108:109], s[18:19] op_sel_hi:[1,0]
	v_pk_mul_f32 v[102:103], v[110:111], v[102:103]
	v_pk_mul_f32 v[100:101], v[108:109], v[100:101]
	v_pk_mul_f32 v[108:109], v[110:111], s[18:19] op_sel_hi:[1,0]
	v_pk_mul_f32 v[110:111], v[104:105], s[18:19] op_sel_hi:[1,0]
	v_pk_mul_f32 v[96:97], v[104:105], v[96:97]
	v_pk_mul_f32 v[104:105], v[106:107], s[18:19] op_sel_hi:[1,0]
	v_pk_mul_f32 v[98:99], v[106:107], v[98:99]
	v_exp_f32_e32 v106, v118
	v_exp_f32_e32 v107, v119
	v_exp_f32_e32 v108, v108
	v_exp_f32_e32 v109, v109
	v_exp_f32_e32 v110, v110
	v_exp_f32_e32 v111, v111
	v_exp_f32_e32 v104, v104
	v_exp_f32_e32 v105, v105
	v_pk_add_f32 v[106:107], v[106:107], 1.0 op_sel_hi:[1,0]
	v_pk_add_f32 v[108:109], v[108:109], 1.0 op_sel_hi:[1,0]
	v_pk_add_f32 v[110:111], v[110:111], 1.0 op_sel_hi:[1,0]
	v_pk_add_f32 v[104:105], v[104:105], 1.0 op_sel_hi:[1,0]
	v_rcp_f32_e32 v106, v106
	v_rcp_f32_e32 v107, v107
	v_rcp_f32_e32 v108, v108
	v_rcp_f32_e32 v109, v109
	v_rcp_f32_e32 v110, v110
	v_rcp_f32_e32 v111, v111
	v_rcp_f32_e32 v104, v104
	v_rcp_f32_e32 v105, v105
	v_pk_mul_f32 v[100:101], v[100:101], v[106:107]
	v_pk_mul_f32 v[102:103], v[102:103], v[108:109]
	v_pk_mul_f32 v[106:107], v[96:97], v[110:111]
	v_pk_mul_f32 v[104:105], v[98:99], v[104:105]
	v_cvt_pk_bf16_f32 v96, v100, v101
	v_cvt_pk_bf16_f32 v97, v102, v103
	v_cvt_pk_bf16_f32 v98, v106, v107
	s_nop 0
	v_cvt_pk_bf16_f32 v99, v104, v105
	global_store_dwordx4 v[114:115], v[96:99], off
	s_nop 1
	v_mov_b32_e32 v97, v227
	s_nop 0
	v_or_b32_e32 v96, 48, v144
	s_waitcnt lgkmcnt(0)
	v_fmamk_f32 v97, v97, 0x3a000000, v158
	v_rsq_f32_e32 v102, v97
	s_nop 1
	v_ashrrev_i32_e32 v97, 31, v96
	v_mad_i64_i32 v[98:99], s[4:5], v112, s42, v[148:149]
	v_lshl_add_u64 v[98:99], v[98:99], 0, v[146:147]
	s_nop 0
	s_nop 1
	s_nop 1
	v_lshl_add_u64 v[100:101], v[96:97], 2, s[10:11]
	s_nop 0
	v_pk_mul_f32 v[94:95], v[94:95], v[102:103] op_sel_hi:[1,0]
	v_pk_mul_f32 v[92:93], v[92:93], v[102:103] op_sel_hi:[1,0]
	v_pk_mul_f32 v[90:91], v[90:91], v[102:103] op_sel_hi:[1,0]
	v_pk_mul_f32 v[88:89], v[88:89], v[102:103] op_sel_hi:[1,0]
	v_pk_mul_f32 v[84:85], v[84:85], v[102:103] op_sel_hi:[1,0]
	v_pk_mul_f32 v[86:87], v[86:87], v[102:103] op_sel_hi:[1,0]
	v_pk_mul_f32 v[80:81], v[80:81], v[102:103] op_sel_hi:[1,0]
	v_pk_mul_f32 v[82:83], v[82:83], v[102:103] op_sel_hi:[1,0]
	v_pk_mul_f32 v[102:103], v[92:93], s[18:19] op_sel_hi:[1,0]
	v_pk_mul_f32 v[86:87], v[94:95], v[86:87]
	v_pk_mul_f32 v[84:85], v[92:93], v[84:85]
	v_pk_mul_f32 v[92:93], v[94:95], s[18:19] op_sel_hi:[1,0]
	v_pk_mul_f32 v[94:95], v[88:89], s[18:19] op_sel_hi:[1,0]
	v_pk_mul_f32 v[80:81], v[88:89], v[80:81]
	v_pk_mul_f32 v[88:89], v[90:91], s[18:19] op_sel_hi:[1,0]
	v_pk_mul_f32 v[82:83], v[90:91], v[82:83]
	v_exp_f32_e32 v90, v102
	v_exp_f32_e32 v91, v103
	v_exp_f32_e32 v92, v92
	v_exp_f32_e32 v93, v93
	v_exp_f32_e32 v94, v94
	v_exp_f32_e32 v95, v95
	v_exp_f32_e32 v88, v88
	v_exp_f32_e32 v89, v89
	v_pk_add_f32 v[90:91], v[90:91], 1.0 op_sel_hi:[1,0]
	v_pk_add_f32 v[92:93], v[92:93], 1.0 op_sel_hi:[1,0]
	v_pk_add_f32 v[94:95], v[94:95], 1.0 op_sel_hi:[1,0]
	v_pk_add_f32 v[88:89], v[88:89], 1.0 op_sel_hi:[1,0]
	v_rcp_f32_e32 v90, v90
	v_rcp_f32_e32 v91, v91
	v_rcp_f32_e32 v92, v92
	v_rcp_f32_e32 v93, v93
	v_rcp_f32_e32 v94, v94
	v_rcp_f32_e32 v95, v95
	v_rcp_f32_e32 v88, v88
	v_rcp_f32_e32 v89, v89
	v_pk_mul_f32 v[84:85], v[84:85], v[90:91]
	v_pk_mul_f32 v[86:87], v[86:87], v[92:93]
	v_pk_mul_f32 v[90:91], v[80:81], v[94:95]
	v_pk_mul_f32 v[88:89], v[82:83], v[88:89]
	v_cvt_pk_bf16_f32 v80, v84, v85
	v_cvt_pk_bf16_f32 v81, v86, v87
	v_cvt_pk_bf16_f32 v82, v90, v91
	s_nop 0
	v_cvt_pk_bf16_f32 v83, v88, v89
	global_store_dwordx4 v[98:99], v[80:83], off
	s_nop 1
	v_mov_b32_e32 v80, v228
	s_waitcnt lgkmcnt(0)
	v_fmamk_f32 v80, v80, 0x3a000000, v158
	v_rsq_f32_e32 v82, v80
	s_nop 1
	v_mad_i64_i32 v[80:81], s[4:5], v96, s42, v[148:149]
	v_lshl_add_u64 v[80:81], v[80:81], 0, v[146:147]
	s_nop 1
	s_nop 1
	s_nop 1
	s_nop 0
	v_pk_mul_f32 v[78:79], v[78:79], v[82:83] op_sel_hi:[1,0]
	v_pk_mul_f32 v[76:77], v[76:77], v[82:83] op_sel_hi:[1,0]
	v_pk_mul_f32 v[74:75], v[74:75], v[82:83] op_sel_hi:[1,0]
	v_pk_mul_f32 v[72:73], v[72:73], v[82:83] op_sel_hi:[1,0]
	v_pk_mul_f32 v[68:69], v[68:69], v[82:83] op_sel_hi:[1,0]
	v_pk_mul_f32 v[70:71], v[70:71], v[82:83] op_sel_hi:[1,0]
	v_pk_mul_f32 v[64:65], v[64:65], v[82:83] op_sel_hi:[1,0]
	v_pk_mul_f32 v[66:67], v[66:67], v[82:83] op_sel_hi:[1,0]
	v_pk_mul_f32 v[82:83], v[76:77], s[18:19] op_sel_hi:[1,0]
	v_pk_mul_f32 v[70:71], v[78:79], v[70:71]
	v_pk_mul_f32 v[68:69], v[76:77], v[68:69]
	v_pk_mul_f32 v[76:77], v[78:79], s[18:19] op_sel_hi:[1,0]
	v_pk_mul_f32 v[78:79], v[72:73], s[18:19] op_sel_hi:[1,0]
	v_pk_mul_f32 v[64:65], v[72:73], v[64:65]
	v_pk_mul_f32 v[72:73], v[74:75], s[18:19] op_sel_hi:[1,0]
	v_pk_mul_f32 v[66:67], v[74:75], v[66:67]
	v_exp_f32_e32 v74, v82
	v_exp_f32_e32 v75, v83
	v_exp_f32_e32 v76, v76
	v_exp_f32_e32 v77, v77
	v_exp_f32_e32 v78, v78
	v_exp_f32_e32 v79, v79
	v_exp_f32_e32 v72, v72
	v_exp_f32_e32 v73, v73
	v_pk_add_f32 v[74:75], v[74:75], 1.0 op_sel_hi:[1,0]
	v_pk_add_f32 v[76:77], v[76:77], 1.0 op_sel_hi:[1,0]
	v_pk_add_f32 v[78:79], v[78:79], 1.0 op_sel_hi:[1,0]
	v_pk_add_f32 v[72:73], v[72:73], 1.0 op_sel_hi:[1,0]
	v_rcp_f32_e32 v74, v74
	v_rcp_f32_e32 v75, v75
	v_rcp_f32_e32 v76, v76
	v_rcp_f32_e32 v77, v77
	v_rcp_f32_e32 v78, v78
	v_rcp_f32_e32 v79, v79
	v_rcp_f32_e32 v72, v72
	v_rcp_f32_e32 v73, v73
	v_pk_mul_f32 v[68:69], v[68:69], v[74:75]
	v_pk_mul_f32 v[70:71], v[70:71], v[76:77]
	v_pk_mul_f32 v[74:75], v[64:65], v[78:79]
	v_pk_mul_f32 v[72:73], v[66:67], v[72:73]
	v_cvt_pk_bf16_f32 v64, v68, v69
	v_cvt_pk_bf16_f32 v65, v70, v71
	v_cvt_pk_bf16_f32 v66, v74, v75
	s_nop 0
	v_cvt_pk_bf16_f32 v67, v72, v73
	global_store_dwordx4 v[80:81], v[64:67], off
	s_nop 1
	v_mov_b32_e32 v64, v229
	s_waitcnt lgkmcnt(0)
	v_fmamk_f32 v64, v64, 0x3a000000, v158
	v_rsq_f32_e32 v66, v64
	s_nop 1
	v_add_u32_e32 v64, 0x80, v144
	v_mad_i64_i32 v[64:65], s[4:5], v64, s42, v[148:149]
	v_lshl_add_u64 v[64:65], v[64:65], 0, v[146:147]
	s_nop 0
	s_nop 1
	s_nop 1
	s_nop 0
	v_pk_mul_f32 v[62:63], v[62:63], v[66:67] op_sel_hi:[1,0]
	v_pk_mul_f32 v[60:61], v[60:61], v[66:67] op_sel_hi:[1,0]
	v_pk_mul_f32 v[58:59], v[58:59], v[66:67] op_sel_hi:[1,0]
	v_pk_mul_f32 v[56:57], v[56:57], v[66:67] op_sel_hi:[1,0]
	v_pk_mul_f32 v[52:53], v[52:53], v[66:67] op_sel_hi:[1,0]
	v_pk_mul_f32 v[54:55], v[54:55], v[66:67] op_sel_hi:[1,0]
	v_pk_mul_f32 v[48:49], v[48:49], v[66:67] op_sel_hi:[1,0]
	v_pk_mul_f32 v[50:51], v[50:51], v[66:67] op_sel_hi:[1,0]
	v_pk_mul_f32 v[66:67], v[60:61], s[18:19] op_sel_hi:[1,0]
	v_pk_mul_f32 v[54:55], v[62:63], v[54:55]
	v_pk_mul_f32 v[52:53], v[60:61], v[52:53]
	v_pk_mul_f32 v[60:61], v[62:63], s[18:19] op_sel_hi:[1,0]
	v_pk_mul_f32 v[62:63], v[56:57], s[18:19] op_sel_hi:[1,0]
	v_pk_mul_f32 v[48:49], v[56:57], v[48:49]
	v_pk_mul_f32 v[56:57], v[58:59], s[18:19] op_sel_hi:[1,0]
	v_pk_mul_f32 v[50:51], v[58:59], v[50:51]
	v_exp_f32_e32 v58, v66
	v_exp_f32_e32 v59, v67
	v_exp_f32_e32 v60, v60
	v_exp_f32_e32 v61, v61
	v_exp_f32_e32 v62, v62
	v_exp_f32_e32 v63, v63
	v_exp_f32_e32 v56, v56
	v_exp_f32_e32 v57, v57
	v_pk_add_f32 v[58:59], v[58:59], 1.0 op_sel_hi:[1,0]
	v_pk_add_f32 v[60:61], v[60:61], 1.0 op_sel_hi:[1,0]
	v_pk_add_f32 v[62:63], v[62:63], 1.0 op_sel_hi:[1,0]
	v_pk_add_f32 v[56:57], v[56:57], 1.0 op_sel_hi:[1,0]
	v_rcp_f32_e32 v58, v58
	v_rcp_f32_e32 v59, v59
	v_rcp_f32_e32 v60, v60
	v_rcp_f32_e32 v61, v61
	v_rcp_f32_e32 v62, v62
	v_rcp_f32_e32 v63, v63
	v_rcp_f32_e32 v56, v56
	v_rcp_f32_e32 v57, v57
	v_pk_mul_f32 v[52:53], v[52:53], v[58:59]
	v_pk_mul_f32 v[54:55], v[54:55], v[60:61]
	v_pk_mul_f32 v[58:59], v[48:49], v[62:63]
	v_pk_mul_f32 v[56:57], v[50:51], v[56:57]
	v_cvt_pk_bf16_f32 v48, v52, v53
	v_cvt_pk_bf16_f32 v49, v54, v55
	v_cvt_pk_bf16_f32 v50, v58, v59
	s_nop 0
	v_cvt_pk_bf16_f32 v51, v56, v57
	global_store_dwordx4 v[64:65], v[48:51], off
	s_nop 1
	v_mov_b32_e32 v48, v230
	s_waitcnt lgkmcnt(0)
	v_fmamk_f32 v48, v48, 0x3a000000, v158
	v_rsq_f32_e32 v50, v48
	s_nop 1
	v_add_u32_e32 v48, 0x90, v144
	v_mad_i64_i32 v[48:49], s[4:5], v48, s42, v[148:149]
	v_lshl_add_u64 v[48:49], v[48:49], 0, v[146:147]
	s_nop 0
	s_nop 1
	s_nop 1
	s_nop 0
	v_pk_mul_f32 v[46:47], v[46:47], v[50:51] op_sel_hi:[1,0]
	v_pk_mul_f32 v[44:45], v[44:45], v[50:51] op_sel_hi:[1,0]
	v_pk_mul_f32 v[42:43], v[42:43], v[50:51] op_sel_hi:[1,0]
	v_pk_mul_f32 v[40:41], v[40:41], v[50:51] op_sel_hi:[1,0]
	v_pk_mul_f32 v[36:37], v[36:37], v[50:51] op_sel_hi:[1,0]
	v_pk_mul_f32 v[38:39], v[38:39], v[50:51] op_sel_hi:[1,0]
	v_pk_mul_f32 v[32:33], v[32:33], v[50:51] op_sel_hi:[1,0]
	v_pk_mul_f32 v[34:35], v[34:35], v[50:51] op_sel_hi:[1,0]
	v_pk_mul_f32 v[50:51], v[44:45], s[18:19] op_sel_hi:[1,0]
	v_pk_mul_f32 v[38:39], v[46:47], v[38:39]
	v_pk_mul_f32 v[36:37], v[44:45], v[36:37]
	v_pk_mul_f32 v[44:45], v[46:47], s[18:19] op_sel_hi:[1,0]
	v_pk_mul_f32 v[46:47], v[40:41], s[18:19] op_sel_hi:[1,0]
	v_pk_mul_f32 v[32:33], v[40:41], v[32:33]
	v_pk_mul_f32 v[40:41], v[42:43], s[18:19] op_sel_hi:[1,0]
	v_pk_mul_f32 v[34:35], v[42:43], v[34:35]
	v_exp_f32_e32 v42, v50
	v_exp_f32_e32 v43, v51
	v_exp_f32_e32 v44, v44
	v_exp_f32_e32 v45, v45
	v_exp_f32_e32 v46, v46
	v_exp_f32_e32 v47, v47
	v_exp_f32_e32 v40, v40
	v_exp_f32_e32 v41, v41
	v_pk_add_f32 v[42:43], v[42:43], 1.0 op_sel_hi:[1,0]
	v_pk_add_f32 v[44:45], v[44:45], 1.0 op_sel_hi:[1,0]
	v_pk_add_f32 v[46:47], v[46:47], 1.0 op_sel_hi:[1,0]
	v_pk_add_f32 v[40:41], v[40:41], 1.0 op_sel_hi:[1,0]
	v_rcp_f32_e32 v42, v42
	v_rcp_f32_e32 v43, v43
	v_rcp_f32_e32 v44, v44
	v_rcp_f32_e32 v45, v45
	v_rcp_f32_e32 v46, v46
	v_rcp_f32_e32 v47, v47
	v_rcp_f32_e32 v40, v40
	v_rcp_f32_e32 v41, v41
	v_pk_mul_f32 v[36:37], v[36:37], v[42:43]
	v_pk_mul_f32 v[38:39], v[38:39], v[44:45]
	v_pk_mul_f32 v[42:43], v[32:33], v[46:47]
	v_pk_mul_f32 v[40:41], v[34:35], v[40:41]
	v_cvt_pk_bf16_f32 v32, v36, v37
	v_cvt_pk_bf16_f32 v33, v38, v39
	v_cvt_pk_bf16_f32 v34, v42, v43
	s_nop 0
	v_cvt_pk_bf16_f32 v35, v40, v41
	global_store_dwordx4 v[48:49], v[32:35], off
	s_nop 1
	v_mov_b32_e32 v32, v231
	s_waitcnt lgkmcnt(0)
	v_fmamk_f32 v32, v32, 0x3a000000, v158
	v_rsq_f32_e32 v34, v32
	s_nop 1
	v_add_u32_e32 v32, 0xa0, v144
	v_mad_i64_i32 v[32:33], s[4:5], v32, s42, v[148:149]
	v_lshl_add_u64 v[32:33], v[32:33], 0, v[146:147]
	s_nop 0
	s_nop 1
	s_nop 1
	s_nop 0
	v_pk_mul_f32 v[30:31], v[30:31], v[34:35] op_sel_hi:[1,0]
	v_pk_mul_f32 v[28:29], v[28:29], v[34:35] op_sel_hi:[1,0]
	v_pk_mul_f32 v[26:27], v[26:27], v[34:35] op_sel_hi:[1,0]
	v_pk_mul_f32 v[24:25], v[24:25], v[34:35] op_sel_hi:[1,0]
	v_pk_mul_f32 v[20:21], v[20:21], v[34:35] op_sel_hi:[1,0]
	v_pk_mul_f32 v[22:23], v[22:23], v[34:35] op_sel_hi:[1,0]
	v_pk_mul_f32 v[16:17], v[16:17], v[34:35] op_sel_hi:[1,0]
	v_pk_mul_f32 v[18:19], v[18:19], v[34:35] op_sel_hi:[1,0]
	v_pk_mul_f32 v[34:35], v[28:29], s[18:19] op_sel_hi:[1,0]
	v_pk_mul_f32 v[22:23], v[30:31], v[22:23]
	v_pk_mul_f32 v[20:21], v[28:29], v[20:21]
	v_pk_mul_f32 v[28:29], v[30:31], s[18:19] op_sel_hi:[1,0]
	v_pk_mul_f32 v[30:31], v[24:25], s[18:19] op_sel_hi:[1,0]
	v_pk_mul_f32 v[16:17], v[24:25], v[16:17]
	v_pk_mul_f32 v[24:25], v[26:27], s[18:19] op_sel_hi:[1,0]
	v_pk_mul_f32 v[18:19], v[26:27], v[18:19]
	v_exp_f32_e32 v26, v34
	v_exp_f32_e32 v27, v35
	v_exp_f32_e32 v28, v28
	v_exp_f32_e32 v29, v29
	v_exp_f32_e32 v30, v30
	v_exp_f32_e32 v31, v31
	v_exp_f32_e32 v24, v24
	v_exp_f32_e32 v25, v25
	v_pk_add_f32 v[26:27], v[26:27], 1.0 op_sel_hi:[1,0]
	v_pk_add_f32 v[28:29], v[28:29], 1.0 op_sel_hi:[1,0]
	v_pk_add_f32 v[30:31], v[30:31], 1.0 op_sel_hi:[1,0]
	v_pk_add_f32 v[24:25], v[24:25], 1.0 op_sel_hi:[1,0]
	v_rcp_f32_e32 v26, v26
	v_rcp_f32_e32 v27, v27
	v_rcp_f32_e32 v28, v28
	v_rcp_f32_e32 v29, v29
	v_rcp_f32_e32 v30, v30
	v_rcp_f32_e32 v31, v31
	v_rcp_f32_e32 v24, v24
	v_rcp_f32_e32 v25, v25
	v_pk_mul_f32 v[20:21], v[20:21], v[26:27]
	v_pk_mul_f32 v[22:23], v[22:23], v[28:29]
	v_pk_mul_f32 v[26:27], v[16:17], v[30:31]
	v_pk_mul_f32 v[24:25], v[18:19], v[24:25]
	v_cvt_pk_bf16_f32 v16, v20, v21
	v_cvt_pk_bf16_f32 v17, v22, v23
	v_cvt_pk_bf16_f32 v18, v26, v27
	s_nop 0
	v_cvt_pk_bf16_f32 v19, v24, v25
	global_store_dwordx4 v[32:33], v[16:19], off
	s_nop 1
	v_mov_b32_e32 v16, v232
	s_nop 0
	v_add_u32_e32 v17, 0xb0, v144
	s_waitcnt lgkmcnt(0)
	v_fmamk_f32 v16, v16, 0x3a000000, v158
	v_rsq_f32_e32 v18, v16
	s_nop 1
	v_mad_i64_i32 v[16:17], s[4:5], v17, s42, v[148:149]
	v_lshl_add_u64 v[16:17], v[16:17], 0, v[146:147]
	s_nop 1
	s_nop 1
	s_nop 1
	s_mov_b64 s[4:5], -1
	s_nop 0
	v_pk_mul_f32 v[14:15], v[14:15], v[18:19] op_sel_hi:[1,0]
	v_pk_mul_f32 v[12:13], v[12:13], v[18:19] op_sel_hi:[1,0]
	v_pk_mul_f32 v[10:11], v[10:11], v[18:19] op_sel_hi:[1,0]
	v_pk_mul_f32 v[8:9], v[8:9], v[18:19] op_sel_hi:[1,0]
	v_pk_mul_f32 v[4:5], v[4:5], v[18:19] op_sel_hi:[1,0]
	v_pk_mul_f32 v[6:7], v[6:7], v[18:19] op_sel_hi:[1,0]
	v_pk_mul_f32 v[0:1], v[0:1], v[18:19] op_sel_hi:[1,0]
	v_pk_mul_f32 v[2:3], v[2:3], v[18:19] op_sel_hi:[1,0]
	v_pk_mul_f32 v[18:19], v[12:13], s[18:19] op_sel_hi:[1,0]
	v_pk_mul_f32 v[6:7], v[14:15], v[6:7]
	v_pk_mul_f32 v[4:5], v[12:13], v[4:5]
	v_pk_mul_f32 v[12:13], v[14:15], s[18:19] op_sel_hi:[1,0]
	v_pk_mul_f32 v[14:15], v[8:9], s[18:19] op_sel_hi:[1,0]
	v_pk_mul_f32 v[0:1], v[8:9], v[0:1]
	v_pk_mul_f32 v[8:9], v[10:11], s[18:19] op_sel_hi:[1,0]
	v_pk_mul_f32 v[2:3], v[10:11], v[2:3]
	v_exp_f32_e32 v10, v18
	v_exp_f32_e32 v11, v19
	v_exp_f32_e32 v12, v12
	v_exp_f32_e32 v13, v13
	v_exp_f32_e32 v14, v14
	v_exp_f32_e32 v15, v15
	v_exp_f32_e32 v8, v8
	v_exp_f32_e32 v9, v9
	v_pk_add_f32 v[10:11], v[10:11], 1.0 op_sel_hi:[1,0]
	v_pk_add_f32 v[12:13], v[12:13], 1.0 op_sel_hi:[1,0]
	v_pk_add_f32 v[14:15], v[14:15], 1.0 op_sel_hi:[1,0]
	v_pk_add_f32 v[8:9], v[8:9], 1.0 op_sel_hi:[1,0]
	v_rcp_f32_e32 v10, v10
	v_rcp_f32_e32 v11, v11
	v_rcp_f32_e32 v12, v12
	v_rcp_f32_e32 v13, v13
	v_rcp_f32_e32 v14, v14
	v_rcp_f32_e32 v15, v15
	v_rcp_f32_e32 v8, v8
	v_rcp_f32_e32 v9, v9
	s_andn2_b64 vcc, exec, s[6:7]
	v_pk_mul_f32 v[4:5], v[4:5], v[10:11]
	v_pk_mul_f32 v[6:7], v[6:7], v[12:13]
	v_pk_mul_f32 v[10:11], v[0:1], v[14:15]
	v_pk_mul_f32 v[8:9], v[2:3], v[8:9]
	v_cvt_pk_bf16_f32 v0, v4, v5
	v_cvt_pk_bf16_f32 v1, v6, v7
	v_cvt_pk_bf16_f32 v2, v10, v11
	s_nop 0
	v_cvt_pk_bf16_f32 v3, v8, v9
	global_store_dwordx4 v[16:17], v[0:3], off
	s_cbranch_vccnz .LBB0_1406
	s_and_b64 vcc, exec, s[60:61]
	s_cbranch_vccnz .LBB0_1405
	s_barrier
	s_branch .LBB0_1405
